# DA item epilogue (main items): lanes l and l+32 exchange halves (v_permlane32_swap), 8 x dwordx4 instead of 16 x dwordx2 row-per-lane stores
# speedup vs baseline: 1.0084x; 1.0002x over previous
.LBB0_302:
	s_andn2_b64 vcc, exec, s[2:3]
	s_waitcnt lgkmcnt(0)
	s_barrier
	s_cbranch_vccnz .LBB0_279
	v_readlane_b32 s64, v239, 0
	ds_read2st64_b32 v[96:97], v2 offset1:1
	ds_read2st64_b32 v[4:5], v2 offset0:2 offset1:3
	ds_read2st64_b32 v[98:99], v2 offset0:4 offset1:5
	ds_read2st64_b32 v[100:101], v2 offset0:6 offset1:7
	ds_read2st64_b32 v[102:103], v2 offset0:8 offset1:9
	ds_read2st64_b32 v[104:105], v2 offset0:10 offset1:11
	ds_read2st64_b32 v[106:107], v2 offset0:12 offset1:13
	ds_read2st64_b32 v[108:109], v2 offset0:14 offset1:15
	ds_read2st64_b32 v[110:111], v2 offset0:16 offset1:17
	ds_read2st64_b32 v[112:113], v2 offset0:18 offset1:19
	ds_read2st64_b32 v[114:115], v2 offset0:20 offset1:21
	ds_read2st64_b32 v[116:117], v2 offset0:22 offset1:23
	ds_read2st64_b32 v[118:119], v2 offset0:24 offset1:25
	ds_read2st64_b32 v[120:121], v2 offset0:26 offset1:27
	ds_read2st64_b32 v[122:123], v2 offset0:28 offset1:29
	ds_read2st64_b32 v[124:125], v2 offset0:30 offset1:31
	ds_read2st64_b32 v[126:127], v2 offset0:32 offset1:33
	ds_read2st64_b32 v[128:129], v2 offset0:34 offset1:35
	ds_read2st64_b32 v[130:131], v2 offset0:36 offset1:37
	ds_read2st64_b32 v[132:133], v2 offset0:38 offset1:39
	ds_read2st64_b32 v[94:95], v2 offset0:40 offset1:41
	ds_read2st64_b32 v[134:135], v2 offset0:42 offset1:43
	ds_read2st64_b32 v[90:91], v2 offset0:44 offset1:45
	ds_read2st64_b32 v[92:93], v2 offset0:46 offset1:47
	ds_read2st64_b32 v[86:87], v2 offset0:48 offset1:49
	ds_read2st64_b32 v[88:89], v2 offset0:50 offset1:51
	ds_read2st64_b32 v[82:83], v2 offset0:52 offset1:53
	ds_read2st64_b32 v[84:85], v2 offset0:54 offset1:55
	ds_read2st64_b32 v[14:15], v2 offset0:56 offset1:57
	ds_read2st64_b32 v[80:81], v2 offset0:58 offset1:59
	ds_read2st64_b32 v[10:11], v2 offset0:60 offset1:61
	ds_read2st64_b32 v[12:13], v2 offset0:62 offset1:63
	v_readlane_b32 s74, v239, 10
	v_readlane_b32 s75, v239, 11
	s_waitcnt lgkmcnt(14)
	v_pk_fma_f32 v[8:9], v[66:67], v[0:1], v[4:5] op_sel_hi:[1,0,1] neg_lo:[0,0,1] neg_hi:[0,0,1]
	v_pk_fma_f32 v[66:67], v[64:65], v[0:1], v[96:97] op_sel_hi:[1,0,1] neg_lo:[0,0,1] neg_hi:[0,0,1]
	v_mul_f32_e32 v96, v9, v9
	v_mul_f32_e32 v64, v67, v67
	v_pk_fma_f32 v[64:65], v[66:67], v[66:67], v[64:65] op_sel_hi:[1,1,0]
	global_load_dwordx4 v[2:5], v146, s[74:75]
	v_pk_fma_f32 v[64:65], v[8:9], v[8:9], v[64:65]
	v_pk_fma_f32 v[76:77], v[76:77], v[0:1], v[106:107] op_sel_hi:[1,0,1] neg_lo:[0,0,1] neg_hi:[0,0,1]
	v_pk_add_f32 v[96:97], v[64:65], v[96:97] op_sel_hi:[1,0]
	v_pk_fma_f32 v[64:65], v[70:71], v[0:1], v[100:101] op_sel_hi:[1,0,1] neg_lo:[0,0,1] neg_hi:[0,0,1]
	v_pk_fma_f32 v[70:71], v[68:69], v[0:1], v[98:99] op_sel_hi:[1,0,1] neg_lo:[0,0,1] neg_hi:[0,0,1]
	v_pk_fma_f32 v[50:51], v[50:51], v[0:1], v[112:113] op_sel_hi:[1,0,1] neg_lo:[0,0,1] neg_hi:[0,0,1]
	v_pk_fma_f32 v[68:69], v[70:71], v[70:71], v[96:97]
	v_mul_f32_e32 v96, v71, v71
	v_pk_add_f32 v[68:69], v[68:69], v[96:97] op_sel_hi:[1,0]
	v_mul_f32_e32 v96, v65, v65
	v_pk_fma_f32 v[68:69], v[64:65], v[64:65], v[68:69]
	v_pk_fma_f32 v[60:61], v[60:61], v[0:1], v[122:123] op_sel_hi:[1,0,1] neg_lo:[0,0,1] neg_hi:[0,0,1]
	v_pk_add_f32 v[96:97], v[68:69], v[96:97] op_sel_hi:[1,0]
	v_pk_fma_f32 v[68:69], v[74:75], v[0:1], v[104:105] op_sel_hi:[1,0,1] neg_lo:[0,0,1] neg_hi:[0,0,1]
	v_pk_fma_f32 v[74:75], v[72:73], v[0:1], v[102:103] op_sel_hi:[1,0,1] neg_lo:[0,0,1] neg_hi:[0,0,1]
	v_pk_fma_f32 v[34:35], v[34:35], v[0:1], v[128:129] op_sel_hi:[1,0,1] neg_lo:[0,0,1] neg_hi:[0,0,1]
	v_pk_fma_f32 v[72:73], v[74:75], v[74:75], v[96:97]
	v_mul_f32_e32 v96, v75, v75
	v_pk_add_f32 v[72:73], v[72:73], v[96:97] op_sel_hi:[1,0]
	v_mul_f32_e32 v96, v69, v69
	v_pk_fma_f32 v[72:73], v[68:69], v[68:69], v[72:73]
	s_waitcnt lgkmcnt(11)
	v_pk_fma_f32 v[40:41], v[40:41], v[0:1], v[94:95] op_sel_hi:[1,0,1] neg_lo:[0,0,1] neg_hi:[0,0,1]
	v_pk_add_f32 v[96:97], v[72:73], v[96:97] op_sel_hi:[1,0]
	v_pk_fma_f32 v[72:73], v[78:79], v[0:1], v[108:109] op_sel_hi:[1,0,1] neg_lo:[0,0,1] neg_hi:[0,0,1]
	v_pk_fma_f32 v[78:79], v[76:77], v[76:77], v[96:97]
	v_mul_f32_e32 v96, v77, v77
	v_pk_add_f32 v[78:79], v[78:79], v[96:97] op_sel_hi:[1,0]
	v_mul_f32_e32 v96, v73, v73
	v_pk_fma_f32 v[78:79], v[72:73], v[72:73], v[78:79]
	v_mul_f32_e32 v94, v41, v41
	v_pk_add_f32 v[96:97], v[78:79], v[96:97] op_sel_hi:[1,0]
	v_pk_fma_f32 v[78:79], v[48:49], v[0:1], v[110:111] op_sel_hi:[1,0,1] neg_lo:[0,0,1] neg_hi:[0,0,1]
	s_waitcnt lgkmcnt(9)
	v_pk_fma_f32 v[44:45], v[44:45], v[0:1], v[90:91] op_sel_hi:[1,0,1] neg_lo:[0,0,1] neg_hi:[0,0,1]
	v_pk_fma_f32 v[48:49], v[78:79], v[78:79], v[96:97]
	v_mul_f32_e32 v96, v79, v79
	v_pk_add_f32 v[48:49], v[48:49], v[96:97] op_sel_hi:[1,0]
	v_mul_f32_e32 v96, v51, v51
	v_pk_fma_f32 v[48:49], v[50:51], v[50:51], v[48:49]
	v_mul_f32_e32 v90, v45, v45
	v_pk_add_f32 v[96:97], v[48:49], v[96:97] op_sel_hi:[1,0]
	v_pk_fma_f32 v[48:49], v[54:55], v[0:1], v[116:117] op_sel_hi:[1,0,1] neg_lo:[0,0,1] neg_hi:[0,0,1]
	v_pk_fma_f32 v[54:55], v[52:53], v[0:1], v[114:115] op_sel_hi:[1,0,1] neg_lo:[0,0,1] neg_hi:[0,0,1]
	s_waitcnt lgkmcnt(8)
	v_pk_fma_f32 v[46:47], v[46:47], v[0:1], v[92:93] op_sel_hi:[1,0,1] neg_lo:[0,0,1] neg_hi:[0,0,1]
	v_pk_fma_f32 v[52:53], v[54:55], v[54:55], v[96:97]
	v_mul_f32_e32 v96, v55, v55
	v_pk_add_f32 v[52:53], v[52:53], v[96:97] op_sel_hi:[1,0]
	v_mul_f32_e32 v96, v49, v49
	v_pk_fma_f32 v[52:53], v[48:49], v[48:49], v[52:53]
	s_waitcnt lgkmcnt(7)
	v_pk_fma_f32 v[16:17], v[16:17], v[0:1], v[86:87] op_sel_hi:[1,0,1] neg_lo:[0,0,1] neg_hi:[0,0,1]
	v_pk_add_f32 v[96:97], v[52:53], v[96:97] op_sel_hi:[1,0]
	v_pk_fma_f32 v[52:53], v[58:59], v[0:1], v[120:121] op_sel_hi:[1,0,1] neg_lo:[0,0,1] neg_hi:[0,0,1]
	v_pk_fma_f32 v[58:59], v[56:57], v[0:1], v[118:119] op_sel_hi:[1,0,1] neg_lo:[0,0,1] neg_hi:[0,0,1]
	v_mul_f32_e32 v86, v17, v17
	v_pk_fma_f32 v[56:57], v[58:59], v[58:59], v[96:97]
	v_mul_f32_e32 v96, v59, v59
	v_pk_add_f32 v[56:57], v[56:57], v[96:97] op_sel_hi:[1,0]
	v_mul_f32_e32 v96, v53, v53
	v_pk_fma_f32 v[56:57], v[52:53], v[52:53], v[56:57]
	s_waitcnt lgkmcnt(6)
	v_pk_fma_f32 v[18:19], v[18:19], v[0:1], v[88:89] op_sel_hi:[1,0,1] neg_lo:[0,0,1] neg_hi:[0,0,1]
	v_pk_add_f32 v[96:97], v[56:57], v[96:97] op_sel_hi:[1,0]
	v_pk_fma_f32 v[56:57], v[62:63], v[0:1], v[124:125] op_sel_hi:[1,0,1] neg_lo:[0,0,1] neg_hi:[0,0,1]
	v_pk_fma_f32 v[62:63], v[60:61], v[60:61], v[96:97]
	v_mul_f32_e32 v96, v61, v61
	v_pk_add_f32 v[62:63], v[62:63], v[96:97] op_sel_hi:[1,0]
	v_mul_f32_e32 v96, v57, v57
	v_pk_fma_f32 v[62:63], v[56:57], v[56:57], v[62:63]
	s_waitcnt lgkmcnt(5)
	v_pk_fma_f32 v[20:21], v[20:21], v[0:1], v[82:83] op_sel_hi:[1,0,1] neg_lo:[0,0,1] neg_hi:[0,0,1]
	v_pk_add_f32 v[96:97], v[62:63], v[96:97] op_sel_hi:[1,0]
	v_pk_fma_f32 v[62:63], v[32:33], v[0:1], v[126:127] op_sel_hi:[1,0,1] neg_lo:[0,0,1] neg_hi:[0,0,1]
	v_mul_f32_e32 v82, v21, v21
	v_pk_fma_f32 v[32:33], v[62:63], v[62:63], v[96:97]
	v_mul_f32_e32 v96, v63, v63
	v_pk_add_f32 v[32:33], v[32:33], v[96:97] op_sel_hi:[1,0]
	v_mul_f32_e32 v96, v35, v35
	v_pk_fma_f32 v[32:33], v[34:35], v[34:35], v[32:33]
	s_waitcnt lgkmcnt(4)
	v_pk_fma_f32 v[22:23], v[22:23], v[0:1], v[84:85] op_sel_hi:[1,0,1] neg_lo:[0,0,1] neg_hi:[0,0,1]
	v_pk_add_f32 v[96:97], v[32:33], v[96:97] op_sel_hi:[1,0]
	v_pk_fma_f32 v[32:33], v[38:39], v[0:1], v[132:133] op_sel_hi:[1,0,1] neg_lo:[0,0,1] neg_hi:[0,0,1]
	v_pk_fma_f32 v[38:39], v[36:37], v[0:1], v[130:131] op_sel_hi:[1,0,1] neg_lo:[0,0,1] neg_hi:[0,0,1]
	s_waitcnt lgkmcnt(3)
	v_pk_fma_f32 v[14:15], v[24:25], v[0:1], v[14:15] op_sel_hi:[1,0,1] neg_lo:[0,0,1] neg_hi:[0,0,1]
	v_pk_fma_f32 v[36:37], v[38:39], v[38:39], v[96:97]
	v_mul_f32_e32 v96, v39, v39
	v_pk_add_f32 v[36:37], v[36:37], v[96:97] op_sel_hi:[1,0]
	v_mul_f32_e32 v96, v33, v33
	v_pk_fma_f32 v[36:37], v[32:33], v[32:33], v[36:37]
	s_waitcnt lgkmcnt(2)
	v_pk_fma_f32 v[26:27], v[26:27], v[0:1], v[80:81] op_sel_hi:[1,0,1] neg_lo:[0,0,1] neg_hi:[0,0,1]
	v_pk_add_f32 v[96:97], v[36:37], v[96:97] op_sel_hi:[1,0]
	v_pk_fma_f32 v[36:37], v[42:43], v[0:1], v[134:135] op_sel_hi:[1,0,1] neg_lo:[0,0,1] neg_hi:[0,0,1]
	v_pk_fma_f32 v[42:43], v[40:41], v[40:41], v[96:97]
	s_waitcnt lgkmcnt(1)
	v_pk_fma_f32 v[10:11], v[28:29], v[0:1], v[10:11] op_sel_hi:[1,0,1] neg_lo:[0,0,1] neg_hi:[0,0,1]
	v_pk_add_f32 v[42:43], v[42:43], v[94:95] op_sel_hi:[1,0]
	v_mul_f32_e32 v94, v37, v37
	v_pk_fma_f32 v[42:43], v[36:37], v[36:37], v[42:43]
	s_waitcnt lgkmcnt(0)
	v_pk_fma_f32 v[12:13], v[30:31], v[0:1], v[12:13] op_sel_hi:[1,0,1] neg_lo:[0,0,1] neg_hi:[0,0,1]
	v_pk_add_f32 v[42:43], v[42:43], v[94:95] op_sel_hi:[1,0]
	v_mul_f32_e32 v0, v11, v11
	v_pk_fma_f32 v[42:43], v[44:45], v[44:45], v[42:43]
	v_readlane_b32 s52, v239, 32
	v_pk_add_f32 v[42:43], v[42:43], v[90:91] op_sel_hi:[1,0]
	v_mul_f32_e32 v90, v47, v47
	v_pk_fma_f32 v[42:43], v[46:47], v[46:47], v[42:43]
	v_readlane_b32 s53, v239, 33
	v_pk_add_f32 v[42:43], v[42:43], v[90:91] op_sel_hi:[1,0]
	s_lshl_b32 s0, s49, 1
	v_pk_fma_f32 v[42:43], v[16:17], v[16:17], v[42:43]
	v_lshl_add_u64 v[6:7], v[158:159], 1, s[52:53]
	v_pk_add_f32 v[42:43], v[42:43], v[86:87] op_sel_hi:[1,0]
	v_mul_f32_e32 v86, v19, v19
	v_pk_fma_f32 v[42:43], v[18:19], v[18:19], v[42:43]
	v_lshl_add_u64 v[6:7], v[6:7], 0, s[0:1]
	v_pk_add_f32 v[42:43], v[42:43], v[86:87] op_sel_hi:[1,0]
	v_readlane_b32 s54, v239, 34
	v_pk_fma_f32 v[42:43], v[20:21], v[20:21], v[42:43]
	v_readlane_b32 s55, v239, 35
	v_pk_add_f32 v[42:43], v[42:43], v[82:83] op_sel_hi:[1,0]
	v_mul_f32_e32 v82, v23, v23
	v_pk_fma_f32 v[42:43], v[22:23], v[22:23], v[42:43]
	v_readlane_b32 s56, v239, 36
	v_pk_add_f32 v[42:43], v[42:43], v[82:83] op_sel_hi:[1,0]
	v_readlane_b32 s57, v239, 37
	v_pk_fma_f32 v[24:25], v[14:15], v[14:15], v[42:43]
	v_mul_f32_e32 v42, v15, v15
	v_pk_add_f32 v[24:25], v[24:25], v[42:43] op_sel_hi:[1,0]
	v_mul_f32_e32 v42, v27, v27
	v_pk_fma_f32 v[24:25], v[26:27], v[26:27], v[24:25]
	v_readlane_b32 s58, v239, 38
	v_pk_add_f32 v[24:25], v[24:25], v[42:43] op_sel_hi:[1,0]
	v_readlane_b32 s59, v239, 39
	v_pk_fma_f32 v[24:25], v[10:11], v[10:11], v[24:25]
	v_readlane_b32 s65, v239, 1
	v_pk_add_f32 v[24:25], v[24:25], v[0:1] op_sel_hi:[1,0]
	v_mul_f32_e32 v0, v13, v13
	v_pk_fma_f32 v[24:25], v[12:13], v[12:13], v[24:25]
	v_readlane_b32 s66, v239, 2
	v_pk_add_f32 v[24:25], v[24:25], v[0:1] op_sel_hi:[1,0]
	v_readlane_b32 s67, v239, 3
	v_mov_b32_e32 v0, v24
	s_nop 1
	v_permlane32_swap_b32_e32 v24, v0
	v_add_f32_e32 v0, v24, v0
	v_fmamk_f32 v0, v0, 0x3c000000, v157
	v_mul_f32_e32 v24, 0x4b800000, v0
	v_cmp_gt_f32_e32 vcc, s46, v0
	v_readlane_b32 s68, v239, 4
	v_readlane_b32 s69, v239, 5
	v_cndmask_b32_e32 v0, v0, v24, vcc
	v_rsq_f32_e32 v24, v0
	v_lshlrev_b32_e32 v0, 3, v168
	v_lshl_add_u64 v[6:7], v[6:7], 0, v[0:1]
	v_readlane_b32 s70, v239, 6
	v_mul_f32_e32 v0, 0x45800000, v24
	v_cndmask_b32_e32 v0, v24, v0, vcc
	v_mul_f32_e32 v0, 0x3f4ccccd, v0
	v_pk_mul_f32 v[24:25], v[66:67], v[0:1] op_sel_hi:[1,0]
	v_pk_mul_f32 v[8:9], v[8:9], v[0:1] op_sel_hi:[1,0]
	s_waitcnt vmcnt(0)
	v_mbcnt_lo_u32_b32 v246, -1, 0
	v_mbcnt_hi_u32_b32 v246, -1, v246
	v_lshrrev_b32_e32 v246, 5, v246
	v_lshlrev_b32_e32 v246, 3, v246
	v_mov_b32_e32 v247, 0
	v_lshl_add_u64 v[6:7], v[6:7], 0, v[246:247]
	v_pk_mul_f32 v[2:3], v[2:3], v[24:25]
	v_pk_mul_f32 v[4:5], v[4:5], v[8:9]
	v_cvt_pk_bf16_f32 v2, v2, v3
	v_cvt_pk_bf16_f32 v3, v4, v5
	global_load_dwordx4 v[80:83], v146, s[74:75] offset:32
	global_load_dwordx4 v[84:87], v146, s[74:75] offset:64
	global_load_dwordx4 v[88:91], v146, s[74:75] offset:96
	global_load_dwordx4 v[92:95], v146, s[74:75] offset:128
	global_load_dwordx4 v[96:99], v146, s[74:75] offset:160
	global_load_dwordx4 v[100:103], v146, s[74:75] offset:192
	global_load_dwordx4 v[104:107], v146, s[74:75] offset:224
	global_load_dwordx4 v[108:111], v146, s[74:75] offset:256
	global_load_dwordx4 v[112:115], v146, s[74:75] offset:288
	global_load_dwordx4 v[116:119], v146, s[74:75] offset:320
	global_load_dwordx4 v[120:123], v146, s[74:75] offset:352
	global_load_dwordx4 v[124:127], v146, s[74:75] offset:384
	global_load_dwordx4 v[128:131], v146, s[74:75] offset:416
	global_load_dwordx4 v[132:135], v146, s[74:75] offset:448
	global_load_dwordx4 v[240:243], v146, s[74:75] offset:480
	v_pk_mul_f32 v[8:9], v[70:71], v[0:1] op_sel_hi:[1,0]
	v_pk_mul_f32 v[24:25], v[68:69], v[0:1] op_sel_hi:[1,0]
	v_readlane_b32 s71, v239, 7
	v_readlane_b32 s72, v239, 8
	v_readlane_b32 s73, v239, 9
	v_readlane_b32 s76, v239, 12
	v_readlane_b32 s77, v239, 13
	v_readlane_b32 s78, v239, 14
	v_readlane_b32 s79, v239, 15
	s_waitcnt vmcnt(14)
	v_pk_mul_f32 v[80:81], v[80:81], v[8:9]
	v_pk_mul_f32 v[8:9], v[64:65], v[0:1] op_sel_hi:[1,0]
	v_cvt_pk_bf16_f32 v4, v80, v81
	v_pk_mul_f32 v[82:83], v[82:83], v[8:9]
	v_pk_mul_f32 v[8:9], v[74:75], v[0:1] op_sel_hi:[1,0]
	v_cvt_pk_bf16_f32 v5, v82, v83
	s_nop 1
	v_permlane32_swap_b32_e32 v2, v4
	v_permlane32_swap_b32_e32 v3, v5
	global_store_dwordx4 v[6:7], v[2:5], off
	s_waitcnt vmcnt(14)
	v_pk_mul_f32 v[84:85], v[8:9], v[84:85]
	v_pk_mul_f32 v[86:87], v[24:25], v[86:87]
	v_cvt_pk_bf16_f32 v84, v84, v85
	v_cvt_pk_bf16_f32 v85, v86, v87
	v_pk_mul_f32 v[8:9], v[76:77], v[0:1] op_sel_hi:[1,0]
	v_pk_mul_f32 v[24:25], v[72:73], v[0:1] op_sel_hi:[1,0]
	s_waitcnt vmcnt(13)
	v_pk_mul_f32 v[88:89], v[8:9], v[88:89]
	v_pk_mul_f32 v[90:91], v[24:25], v[90:91]
	v_cvt_pk_bf16_f32 v86, v88, v89
	v_cvt_pk_bf16_f32 v87, v90, v91
	s_nop 1
	v_permlane32_swap_b32_e32 v84, v86
	v_permlane32_swap_b32_e32 v85, v87
	global_store_dwordx4 v[6:7], v[84:87], off offset:32
	v_pk_mul_f32 v[8:9], v[78:79], v[0:1] op_sel_hi:[1,0]
	v_pk_mul_f32 v[24:25], v[50:51], v[0:1] op_sel_hi:[1,0]
	s_waitcnt vmcnt(13)
	v_pk_mul_f32 v[92:93], v[8:9], v[92:93]
	v_pk_mul_f32 v[94:95], v[24:25], v[94:95]
	v_cvt_pk_bf16_f32 v92, v92, v93
	v_cvt_pk_bf16_f32 v93, v94, v95
	v_pk_mul_f32 v[8:9], v[54:55], v[0:1] op_sel_hi:[1,0]
	v_pk_mul_f32 v[24:25], v[48:49], v[0:1] op_sel_hi:[1,0]
	s_waitcnt vmcnt(12)
	v_pk_mul_f32 v[96:97], v[8:9], v[96:97]
	v_pk_mul_f32 v[98:99], v[24:25], v[98:99]
	v_cvt_pk_bf16_f32 v94, v96, v97
	v_cvt_pk_bf16_f32 v95, v98, v99
	s_nop 1
	v_permlane32_swap_b32_e32 v92, v94
	v_permlane32_swap_b32_e32 v93, v95
	global_store_dwordx4 v[6:7], v[92:95], off offset:64
	v_pk_mul_f32 v[8:9], v[58:59], v[0:1] op_sel_hi:[1,0]
	v_pk_mul_f32 v[24:25], v[52:53], v[0:1] op_sel_hi:[1,0]
	s_waitcnt vmcnt(12)
	v_pk_mul_f32 v[100:101], v[8:9], v[100:101]
	v_pk_mul_f32 v[102:103], v[24:25], v[102:103]
	v_cvt_pk_bf16_f32 v100, v100, v101
	v_cvt_pk_bf16_f32 v101, v102, v103
	v_pk_mul_f32 v[8:9], v[60:61], v[0:1] op_sel_hi:[1,0]
	v_pk_mul_f32 v[24:25], v[56:57], v[0:1] op_sel_hi:[1,0]
	s_waitcnt vmcnt(11)
	v_pk_mul_f32 v[104:105], v[8:9], v[104:105]
	v_pk_mul_f32 v[106:107], v[24:25], v[106:107]
	v_cvt_pk_bf16_f32 v102, v104, v105
	v_cvt_pk_bf16_f32 v103, v106, v107
	s_nop 1
	v_permlane32_swap_b32_e32 v100, v102
	v_permlane32_swap_b32_e32 v101, v103
	global_store_dwordx4 v[6:7], v[100:103], off offset:96
	v_pk_mul_f32 v[8:9], v[62:63], v[0:1] op_sel_hi:[1,0]
	v_pk_mul_f32 v[24:25], v[34:35], v[0:1] op_sel_hi:[1,0]
	s_waitcnt vmcnt(11)
	v_pk_mul_f32 v[108:109], v[8:9], v[108:109]
	v_pk_mul_f32 v[110:111], v[24:25], v[110:111]
	v_cvt_pk_bf16_f32 v108, v108, v109
	v_cvt_pk_bf16_f32 v109, v110, v111
	v_pk_mul_f32 v[8:9], v[38:39], v[0:1] op_sel_hi:[1,0]
	v_pk_mul_f32 v[24:25], v[32:33], v[0:1] op_sel_hi:[1,0]
	s_waitcnt vmcnt(10)
	v_pk_mul_f32 v[112:113], v[8:9], v[112:113]
	v_pk_mul_f32 v[114:115], v[24:25], v[114:115]
	v_cvt_pk_bf16_f32 v110, v112, v113
	v_cvt_pk_bf16_f32 v111, v114, v115
	s_nop 1
	v_permlane32_swap_b32_e32 v108, v110
	v_permlane32_swap_b32_e32 v109, v111
	global_store_dwordx4 v[6:7], v[108:111], off offset:128
	v_pk_mul_f32 v[8:9], v[40:41], v[0:1] op_sel_hi:[1,0]
	v_pk_mul_f32 v[24:25], v[36:37], v[0:1] op_sel_hi:[1,0]
	s_waitcnt vmcnt(10)
	v_pk_mul_f32 v[116:117], v[8:9], v[116:117]
	v_pk_mul_f32 v[118:119], v[24:25], v[118:119]
	v_cvt_pk_bf16_f32 v116, v116, v117
	v_cvt_pk_bf16_f32 v117, v118, v119
	v_pk_mul_f32 v[8:9], v[44:45], v[0:1] op_sel_hi:[1,0]
	v_pk_mul_f32 v[24:25], v[46:47], v[0:1] op_sel_hi:[1,0]
	s_waitcnt vmcnt(9)
	v_pk_mul_f32 v[120:121], v[8:9], v[120:121]
	v_pk_mul_f32 v[122:123], v[24:25], v[122:123]
	v_cvt_pk_bf16_f32 v118, v120, v121
	v_cvt_pk_bf16_f32 v119, v122, v123
	s_nop 1
	v_permlane32_swap_b32_e32 v116, v118
	v_permlane32_swap_b32_e32 v117, v119
	global_store_dwordx4 v[6:7], v[116:119], off offset:160
	v_pk_mul_f32 v[8:9], v[16:17], v[0:1] op_sel_hi:[1,0]
	v_pk_mul_f32 v[16:17], v[18:19], v[0:1] op_sel_hi:[1,0]
	s_waitcnt vmcnt(9)
	v_pk_mul_f32 v[124:125], v[8:9], v[124:125]
	v_pk_mul_f32 v[126:127], v[16:17], v[126:127]
	v_cvt_pk_bf16_f32 v124, v124, v125
	v_cvt_pk_bf16_f32 v125, v126, v127
	v_pk_mul_f32 v[8:9], v[20:21], v[0:1] op_sel_hi:[1,0]
	v_pk_mul_f32 v[16:17], v[22:23], v[0:1] op_sel_hi:[1,0]
	s_waitcnt vmcnt(8)
	v_pk_mul_f32 v[128:129], v[8:9], v[128:129]
	v_pk_mul_f32 v[130:131], v[16:17], v[130:131]
	v_cvt_pk_bf16_f32 v126, v128, v129
	v_cvt_pk_bf16_f32 v127, v130, v131
	s_nop 1
	v_permlane32_swap_b32_e32 v124, v126
	v_permlane32_swap_b32_e32 v125, v127
	global_store_dwordx4 v[6:7], v[124:127], off offset:192
	v_pk_mul_f32 v[8:9], v[14:15], v[0:1] op_sel_hi:[1,0]
	v_pk_mul_f32 v[14:15], v[26:27], v[0:1] op_sel_hi:[1,0]
	s_waitcnt vmcnt(8)
	v_pk_mul_f32 v[132:133], v[8:9], v[132:133]
	v_pk_mul_f32 v[134:135], v[14:15], v[134:135]
	v_cvt_pk_bf16_f32 v132, v132, v133
	v_cvt_pk_bf16_f32 v133, v134, v135
	v_pk_mul_f32 v[8:9], v[10:11], v[0:1] op_sel_hi:[1,0]
	v_pk_mul_f32 v[10:11], v[12:13], v[0:1] op_sel_hi:[1,0]
	s_waitcnt vmcnt(7)
	v_pk_mul_f32 v[240:241], v[8:9], v[240:241]
	v_pk_mul_f32 v[242:243], v[10:11], v[242:243]
	v_cvt_pk_bf16_f32 v134, v240, v241
	v_cvt_pk_bf16_f32 v135, v242, v243
	s_nop 1
	v_permlane32_swap_b32_e32 v132, v134
	v_permlane32_swap_b32_e32 v133, v135
	global_store_dwordx4 v[6:7], v[132:135], off offset:224
	s_branch .LBB0_279
